# attention sub-blocks: the four K-fragment LDS reads issued up front with counted lgkmcnt waits, the four V-fragment reads prefetched before the VALU section so the PV MFMAs issue back to back; on top
# speedup vs baseline: 1.0074x; 1.0074x over previous
.LBB0_200:
	s_andn2_b64 vcc, exec, s[44:45]
	s_cbranch_vccnz .LBB0_213
	s_add_i32 s44, s91, 64
	s_cmp_gt_i32 s44, s89
	s_cbranch_scc1 .LBB0_213
	s_add_i32 s44, s91, 0x60
	s_cmp_gt_i32 s44, s89
	s_cbranch_scc1 .LBB0_208
	v_add_u32_e32 v33, v83, v116
	ds_read_b128 v[34:37], v33 offset:4096
	v_add_u32_e32 v33, v83, v117
	ds_read_b128 v[128:131], v33 offset:4096
	v_add_u32_e32 v33, v83, v118
	ds_read_b128 v[196:199], v33 offset:4096
	v_add_u32_e32 v33, v83, v119
	ds_read_b128 v[200:203], v33 offset:4096
	v_add_u32_e32 v220, v83, v120
	v_add_u32_e32 v221, v83, v121
	ds_read_b128 v[204:207], v220 offset:8192
	ds_read_b128 v[208:211], v221 offset:8192
	ds_read_b128 v[212:215], v220 offset:12288
	ds_read_b128 v[216:219], v221 offset:12288
	s_add_i32 s46, s91, 0x7f
	s_mov_b64 s[44:45], -1
	s_cmp_ge_i32 s46, s38
	s_waitcnt lgkmcnt(7)
	v_mfma_f32_32x32x16_bf16 v[34:49], v[34:37], v[50:53], 0
	s_waitcnt lgkmcnt(6)
	v_mfma_f32_32x32x16_bf16 v[34:49], v[128:131], v[54:57], v[34:49]
	s_waitcnt lgkmcnt(5)
	v_mfma_f32_32x32x16_bf16 v[34:49], v[196:199], v[62:65], v[34:49]
	s_waitcnt lgkmcnt(4)
	v_mfma_f32_32x32x16_bf16 v[34:49], v[200:203], v[66:69], v[34:49]
	s_nop 11
	v_max_f32_e32 v138, v34, v34
	v_max_f32_e32 v137, v35, v35
	v_max_f32_e32 v136, v36, v36
	v_max_f32_e32 v135, v37, v37
	v_max_f32_e32 v134, v38, v38
	v_max_f32_e32 v133, v39, v39
	v_max_f32_e32 v132, v40, v40
	v_max_f32_e32 v131, v41, v41
	v_max_f32_e32 v130, v42, v42
	v_max_f32_e32 v129, v43, v43
	v_max_f32_e32 v128, v44, v44
	v_max_f32_e32 v127, v45, v45
	v_max_f32_e32 v46, v46, v46
	v_max_f32_e32 v45, v47, v47
	v_max_f32_e32 v44, v48, v48
	v_max_f32_e32 v43, v49, v49
	s_cbranch_scc0 .LBB0_205
	v_min_f32_e32 v33, 0x41700000, v138
	v_exp_f32_e32 v33, v33
	v_min_f32_e32 v34, 0x41700000, v137
	v_exp_f32_e32 v34, v34
	v_cmp_lt_i32_e32 vcc, 0, v126
	v_min_f32_e32 v36, 0x41700000, v135
	v_exp_f32_e32 v36, v36
	v_cndmask_b32_e32 v33, 0, v33, vcc
	v_cmp_lt_i32_e32 vcc, 1, v126
	v_min_f32_e32 v38, 0x41700000, v129
	v_exp_f32_e32 v47, v38
	v_cndmask_b32_e32 v35, 0, v34, vcc
	v_min_f32_e32 v34, 0x41700000, v136
	v_exp_f32_e32 v34, v34
	v_cmp_lt_i32_e32 vcc, 2, v126
	v_min_f32_e32 v48, 0x41700000, v127
	v_exp_f32_e32 v48, v48
	v_cndmask_b32_e32 v39, 0, v34, vcc
	v_cmp_lt_i32_e32 vcc, 3, v126
	v_min_f32_e32 v34, 0x41700000, v134
	v_exp_f32_e32 v34, v34
	v_cndmask_b32_e32 v37, 0, v36, vcc
	v_min_f32_e32 v36, 0x41700000, v133
	v_exp_f32_e32 v36, v36
	v_cmp_lt_i32_e32 vcc, 4, v126
	v_min_f32_e32 v139, 0x41700000, v45
	v_exp_f32_e32 v139, v139
	v_cndmask_b32_e32 v41, 0, v34, vcc
	v_cmp_lt_i32_e32 vcc, 5, v126
	v_min_f32_e32 v34, 0x41700000, v132
	v_exp_f32_e32 v34, v34
	v_cndmask_b32_e32 v40, 0, v36, vcc
	v_min_f32_e32 v36, 0x41700000, v131
	v_exp_f32_e32 v36, v36
	v_cmp_lt_i32_e32 vcc, 6, v126
	v_min_f32_e32 v141, 0x41700000, v43
	v_exp_f32_e32 v141, v141
	v_cndmask_b32_e32 v34, 0, v34, vcc
	v_cmp_lt_i32_e32 vcc, 7, v126
	s_mov_b64 s[44:45], 0
	s_nop 0
	v_cndmask_b32_e32 v42, 0, v36, vcc
	v_min_f32_e32 v36, 0x41700000, v130
	v_exp_f32_e32 v36, v36
	v_cmp_lt_i32_e32 vcc, 8, v126
	s_nop 1
	v_cndmask_b32_e32 v38, 0, v36, vcc
	v_min_f32_e32 v36, 0x41700000, v128
	v_exp_f32_e32 v36, v36
	v_cmp_lt_i32_e32 vcc, 9, v126
	s_nop 1
	v_cndmask_b32_e32 v47, 0, v47, vcc
	v_cmp_lt_i32_e32 vcc, 10, v126
	s_nop 1
	v_cndmask_b32_e32 v49, 0, v36, vcc
	v_min_f32_e32 v36, 0x41700000, v46
	v_exp_f32_e32 v36, v36
	v_cmp_lt_i32_e32 vcc, 11, v126
	s_nop 1
	v_cndmask_b32_e32 v48, 0, v48, vcc
	v_cmp_lt_i32_e32 vcc, 12, v126
	s_nop 1
	v_cndmask_b32_e32 v140, 0, v36, vcc
	v_min_f32_e32 v36, 0x41700000, v44
	v_exp_f32_e32 v36, v36
	v_cmp_lt_i32_e32 vcc, 13, v126
	s_nop 1
	v_cndmask_b32_e32 v139, 0, v139, vcc
	v_cmp_lt_i32_e32 vcc, 14, v126
	s_nop 1
	v_cndmask_b32_e32 v36, 0, v36, vcc
	v_cmp_lt_i32_e32 vcc, 15, v126
	s_nop 1
	v_cndmask_b32_e32 v141, 0, v141, vcc

.LBB0_207:
	v_add_f32_e32 v44, 1.0, v33
	v_add_f32_e32 v46, 1.0, v38
	v_mul_f32_e32 v127, v35, v44
	v_fmac_f32_e32 v44, v44, v35
	v_mul_f32_e32 v128, v47, v46
	v_fmac_f32_e32 v46, v46, v47
	v_mul_f32_e32 v129, v39, v44
	v_fmac_f32_e32 v44, v44, v39
	v_mul_f32_e32 v39, v49, v46
	v_fmac_f32_e32 v46, v46, v49
	v_mul_f32_e32 v49, v37, v44
	v_fmac_f32_e32 v44, v44, v37
	v_mul_f32_e32 v130, v48, v46
	v_fmac_f32_e32 v46, v46, v48
	v_mul_f32_e32 v48, v41, v44
	v_fmac_f32_e32 v44, v44, v41
	v_mul_f32_e32 v131, v140, v46
	v_fmac_f32_e32 v46, v46, v140
	v_mul_f32_e32 v132, v40, v44
	v_fmac_f32_e32 v44, v44, v40
	v_mul_f32_e32 v133, v139, v46
	v_fmac_f32_e32 v46, v46, v139
	v_fma_f32 v35, v44, v34, v44
	v_fma_f32 v37, v46, v36, v46
	v_mul_f32_e32 v134, v42, v35
	v_fmac_f32_e32 v35, v35, v42
	v_mul_f32_e32 v135, v141, v37
	v_fmac_f32_e32 v37, v37, v141
	v_rcp_f32_e32 v45, v35
	v_rcp_f32_e32 v37, v37
	v_and_b32_e32 v41, 64, v191
	v_xor_b32_e32 v40, 32, v191
	v_add_u32_e32 v41, 64, v41
	v_cmp_lt_i32_e32 vcc, v40, v41
	v_mul_f32_e32 v35, v37, v45
	s_nop 0
	v_cndmask_b32_e32 v40, v191, v40, vcc
	v_lshlrev_b32_e32 v40, 2, v40
	ds_bpermute_b32 v40, v40, v35
	v_mul_f32_e32 v35, v95, v35
	s_waitcnt lgkmcnt(0)
	v_mul_f32_e32 v41, v95, v40
	v_cndmask_b32_e64 v47, v95, v41, s[2:3]
	v_pk_mul_f32 v[42:43], v[36:37], v[46:47]
	v_mul_f32_e32 v95, v35, v40
	v_mov_b32_e32 v35, v43
	v_pk_mul_f32 v[40:41], v[34:35], v[44:45]
	v_add_u32_e32 v46, v83, v121
	v_mul_f32_e32 v33, v33, v41
	v_mul_f32_e32 v34, v127, v41
	v_cvt_pk_bf16_f32 v34, v33, v34
	v_mul_f32_e32 v33, v129, v41
	v_mul_f32_e32 v35, v49, v41
	v_cvt_pk_bf16_f32 v35, v33, v35
	v_mul_f32_e32 v33, v48, v41
	v_mul_f32_e32 v36, v132, v41
	v_cvt_pk_bf16_f32 v36, v33, v36
	v_mul_f32_e32 v33, v40, v41
	v_mul_f32_e32 v37, v134, v41
	v_cvt_pk_bf16_f32 v37, v33, v37
	v_mul_f32_e32 v33, v38, v43
	v_mul_f32_e32 v38, v128, v43
	v_cvt_pk_bf16_f32 v38, v33, v38
	v_mul_f32_e32 v33, v39, v43
	v_mul_f32_e32 v39, v130, v43
	v_cvt_pk_bf16_f32 v39, v33, v39
	v_mul_f32_e32 v33, v131, v43
	v_mul_f32_e32 v40, v133, v43
	v_cvt_pk_bf16_f32 v40, v33, v40
	v_mul_f32_e32 v33, v42, v43
	v_mul_f32_e32 v41, v135, v43
	v_cvt_pk_bf16_f32 v41, v33, v41
	v_add_u32_e32 v33, v83, v120
	s_nop 1
	s_waitcnt lgkmcnt(0)
	v_mfma_f32_32x32x16_bf16 v[16:31], v[204:207], v[34:37], v[16:31]
	v_mfma_f32_32x32x16_bf16 v[16:31], v[208:211], v[38:41], v[16:31]
	v_mfma_f32_32x32x16_bf16 v[0:15], v[212:215], v[34:37], v[0:15]
	v_mfma_f32_32x32x16_bf16 v[0:15], v[216:219], v[38:41], v[0:15]
.LBB0_208:
	v_add_u32_e32 v33, v83, v116
	ds_read_b128 v[34:37], v33
	v_add_u32_e32 v33, v83, v117
	ds_read_b128 v[128:131], v33
	v_add_u32_e32 v33, v83, v118
	ds_read_b128 v[222:225], v33
	v_add_u32_e32 v33, v83, v119
	ds_read_b128 v[226:229], v33
	v_add_u32_e32 v246, v83, v122
	v_add_u32_e32 v247, v83, v123
	ds_read_b128 v[230:233], v246 offset:8192
	ds_read_b128 v[234:237], v247 offset:8192
	ds_read_b128 v[238:241], v246 offset:12288
	ds_read_b128 v[242:245], v247 offset:12288
	s_add_i32 s46, s91, 0x5f
	s_mov_b64 s[44:45], -1
	s_cmp_lt_i32 s46, s38
	s_waitcnt lgkmcnt(7)
	v_mfma_f32_32x32x16_bf16 v[34:49], v[34:37], v[50:53], 0
	s_waitcnt lgkmcnt(6)
	v_mfma_f32_32x32x16_bf16 v[34:49], v[128:131], v[54:57], v[34:49]
	s_waitcnt lgkmcnt(5)
	v_mfma_f32_32x32x16_bf16 v[34:49], v[222:225], v[62:65], v[34:49]
	s_waitcnt lgkmcnt(4)
	v_mfma_f32_32x32x16_bf16 v[34:49], v[226:229], v[66:69], v[34:49]
	s_nop 11
	v_max_f32_e32 v138, v34, v34
	v_max_f32_e32 v137, v35, v35
	v_max_f32_e32 v136, v36, v36
	v_max_f32_e32 v135, v37, v37
	v_max_f32_e32 v134, v38, v38
	v_max_f32_e32 v133, v39, v39
	v_max_f32_e32 v132, v40, v40
	v_max_f32_e32 v131, v41, v41
	v_max_f32_e32 v130, v42, v42
	v_max_f32_e32 v129, v43, v43
	v_max_f32_e32 v128, v44, v44
	v_max_f32_e32 v127, v45, v45
	v_max_f32_e32 v46, v46, v46
	v_max_f32_e32 v45, v47, v47
	v_max_f32_e32 v44, v48, v48
	v_max_f32_e32 v43, v49, v49
	s_cbranch_scc1 .LBB0_210
	v_min_f32_e32 v33, 0x41700000, v138
	v_exp_f32_e32 v33, v33
	v_min_f32_e32 v34, 0x41700000, v137
	v_exp_f32_e32 v34, v34
	v_add_u32_e32 v141, 32, v126
	v_cmp_lt_i32_e32 vcc, 0, v141
	v_min_f32_e32 v36, 0x41700000, v135
	v_exp_f32_e32 v36, v36
	v_cndmask_b32_e32 v33, 0, v33, vcc
	v_cmp_lt_i32_e32 vcc, 1, v141
	v_min_f32_e32 v38, 0x41700000, v129
	v_exp_f32_e32 v47, v38
	v_cndmask_b32_e32 v35, 0, v34, vcc
	v_min_f32_e32 v34, 0x41700000, v136
	v_exp_f32_e32 v34, v34
	v_cmp_lt_i32_e32 vcc, 2, v141
	v_min_f32_e32 v48, 0x41700000, v127
	v_exp_f32_e32 v48, v48
	v_cndmask_b32_e32 v39, 0, v34, vcc
	v_cmp_lt_i32_e32 vcc, 3, v141
	v_min_f32_e32 v34, 0x41700000, v134
	v_exp_f32_e32 v34, v34
	v_cndmask_b32_e32 v37, 0, v36, vcc
	v_min_f32_e32 v36, 0x41700000, v133
	v_exp_f32_e32 v36, v36
	v_cmp_lt_i32_e32 vcc, 4, v141
	v_min_f32_e32 v139, 0x41700000, v45
	v_exp_f32_e32 v139, v139
	v_cndmask_b32_e32 v41, 0, v34, vcc
	v_cmp_lt_i32_e32 vcc, 5, v141
	v_min_f32_e32 v34, 0x41700000, v132
	v_exp_f32_e32 v34, v34
	v_cndmask_b32_e32 v40, 0, v36, vcc
	v_min_f32_e32 v36, 0x41700000, v131
	v_exp_f32_e32 v36, v36
	v_cmp_lt_i32_e32 vcc, 6, v141
	v_min_f32_e32 v142, 0x41700000, v43
	v_exp_f32_e32 v142, v142
	v_cndmask_b32_e32 v34, 0, v34, vcc
	v_cmp_lt_i32_e32 vcc, 7, v141
	s_mov_b64 s[44:45], 0
	s_nop 0
	v_cndmask_b32_e32 v42, 0, v36, vcc
	v_min_f32_e32 v36, 0x41700000, v130
	v_exp_f32_e32 v36, v36
	v_cmp_lt_i32_e32 vcc, 8, v141
	s_nop 1
	v_cndmask_b32_e32 v38, 0, v36, vcc
	v_min_f32_e32 v36, 0x41700000, v128
	v_exp_f32_e32 v36, v36
	v_cmp_lt_i32_e32 vcc, 9, v141
	s_nop 1
	v_cndmask_b32_e32 v47, 0, v47, vcc
	v_cmp_lt_i32_e32 vcc, 10, v141
	s_nop 1
	v_cndmask_b32_e32 v49, 0, v36, vcc
	v_min_f32_e32 v36, 0x41700000, v46
	v_exp_f32_e32 v36, v36
	v_cmp_lt_i32_e32 vcc, 11, v141
	s_nop 1
	v_cndmask_b32_e32 v48, 0, v48, vcc
	v_cmp_lt_i32_e32 vcc, 12, v141
	s_nop 1
	v_cndmask_b32_e32 v140, 0, v36, vcc
	v_min_f32_e32 v36, 0x41700000, v44
	v_exp_f32_e32 v36, v36
	v_cmp_lt_i32_e32 vcc, 13, v141
	s_nop 1
	v_cndmask_b32_e32 v139, 0, v139, vcc
	v_cmp_lt_i32_e32 vcc, 14, v141
	s_nop 1
	v_cndmask_b32_e32 v36, 0, v36, vcc
	v_cmp_lt_i32_e32 vcc, 15, v141
	s_nop 1
	v_cndmask_b32_e32 v141, 0, v142, vcc

.LBB0_212:
	v_add_f32_e32 v44, 1.0, v33
	v_add_f32_e32 v46, 1.0, v38
	v_mul_f32_e32 v127, v35, v44
	v_fmac_f32_e32 v44, v44, v35
	v_mul_f32_e32 v128, v47, v46
	v_fmac_f32_e32 v46, v46, v47
	v_mul_f32_e32 v129, v39, v44
	v_fmac_f32_e32 v44, v44, v39
	v_mul_f32_e32 v39, v49, v46
	v_fmac_f32_e32 v46, v46, v49
	v_mul_f32_e32 v49, v37, v44
	v_fmac_f32_e32 v44, v44, v37
	v_mul_f32_e32 v130, v48, v46
	v_fmac_f32_e32 v46, v46, v48
	v_mul_f32_e32 v48, v41, v44
	v_fmac_f32_e32 v44, v44, v41
	v_mul_f32_e32 v131, v140, v46
	v_fmac_f32_e32 v46, v46, v140
	v_mul_f32_e32 v132, v40, v44
	v_fmac_f32_e32 v44, v44, v40
	v_mul_f32_e32 v133, v139, v46
	v_fmac_f32_e32 v46, v46, v139
	v_fma_f32 v35, v44, v34, v44
	v_fma_f32 v37, v46, v36, v46
	v_mul_f32_e32 v134, v42, v35
	v_fmac_f32_e32 v35, v35, v42
	v_mul_f32_e32 v135, v141, v37
	v_fmac_f32_e32 v37, v37, v141
	v_rcp_f32_e32 v45, v35
	v_rcp_f32_e32 v37, v37
	v_and_b32_e32 v40, 64, v191
	v_xor_b32_e32 v35, 32, v191
	v_add_u32_e32 v40, 64, v40
	v_cmp_lt_i32_e32 vcc, v35, v40
	v_mul_f32_e32 v136, v37, v45
	s_nop 0
	v_cndmask_b32_e32 v35, v191, v35, vcc
	v_lshlrev_b32_e32 v35, 2, v35
	ds_bpermute_b32 v137, v35, v136
	s_waitcnt lgkmcnt(0)
	v_mul_f32_e32 v35, v95, v137
	v_cndmask_b32_e64 v47, v95, v35, s[2:3]
	v_pk_mul_f32 v[42:43], v[36:37], v[46:47]
	v_add_u32_e32 v46, v83, v123
	v_mov_b32_e32 v35, v43
	v_pk_mul_f32 v[40:41], v[34:35], v[44:45]
	s_nop 0
	v_mul_f32_e32 v33, v33, v41
	v_mul_f32_e32 v34, v127, v41
	v_cvt_pk_bf16_f32 v34, v33, v34
	v_mul_f32_e32 v33, v129, v41
	v_mul_f32_e32 v35, v49, v41
	v_cvt_pk_bf16_f32 v35, v33, v35
	v_mul_f32_e32 v33, v48, v41
	v_mul_f32_e32 v36, v132, v41
	v_cvt_pk_bf16_f32 v36, v33, v36
	v_mul_f32_e32 v33, v40, v41
	v_mul_f32_e32 v37, v134, v41
	v_cvt_pk_bf16_f32 v37, v33, v37
	v_mul_f32_e32 v33, v38, v43
	v_mul_f32_e32 v38, v128, v43
	v_cvt_pk_bf16_f32 v38, v33, v38
	v_mul_f32_e32 v33, v39, v43
	v_mul_f32_e32 v39, v130, v43
	v_cvt_pk_bf16_f32 v39, v33, v39
	v_mul_f32_e32 v33, v131, v43
	v_mul_f32_e32 v40, v133, v43
	v_cvt_pk_bf16_f32 v40, v33, v40
	v_mul_f32_e32 v33, v42, v43
	v_mul_f32_e32 v41, v135, v43
	v_cvt_pk_bf16_f32 v41, v33, v41
	v_add_u32_e32 v33, v83, v122
	v_mul_f32_e32 v33, v95, v136
	v_mul_f32_e32 v95, v33, v137
	s_nop 1
	s_waitcnt lgkmcnt(0)
	v_mfma_f32_32x32x16_bf16 v[16:31], v[230:233], v[34:37], v[16:31]
	v_mfma_f32_32x32x16_bf16 v[16:31], v[234:237], v[38:41], v[16:31]
	v_mfma_f32_32x32x16_bf16 v[0:15], v[238:241], v[34:37], v[0:15]
	v_mfma_f32_32x32x16_bf16 v[0:15], v[242:245], v[38:41], v[0:15]

.LBB0_220:
	s_andn2_b64 vcc, exec, s[44:45]
	s_cbranch_vccnz .LBB0_233
	s_cmp_gt_i32 s91, s89
	s_cbranch_scc1 .LBB0_233
	s_add_i32 s44, s91, 32
	s_cmp_gt_i32 s44, s89
	v_add_u32_e32 v129, v83, v116
	v_add_u32_e32 v128, v83, v117
	v_add_u32_e32 v127, v83, v118
	v_add_u32_e32 v33, v83, v119
	s_cbranch_scc1 .LBB0_228
	ds_read_b128 v[34:37], v129 offset:20480
	ds_read_b128 v[130:133], v128 offset:20480
	ds_read_b128 v[196:199], v127 offset:20480
	ds_read_b128 v[200:203], v33 offset:20480
	v_add_u32_e32 v220, v83, v120
	v_add_u32_e32 v221, v83, v121
	ds_read_b128 v[204:207], v220 offset:24576
	ds_read_b128 v[208:211], v221 offset:24576
	ds_read_b128 v[212:215], v220 offset:28672
	ds_read_b128 v[216:219], v221 offset:28672
	s_add_i32 s46, s91, 63
	s_mov_b64 s[44:45], -1
	s_cmp_ge_i32 s46, s38
	s_waitcnt lgkmcnt(7)
	v_mfma_f32_32x32x16_bf16 v[34:49], v[34:37], v[50:53], 0
	s_waitcnt lgkmcnt(6)
	v_mfma_f32_32x32x16_bf16 v[34:49], v[130:133], v[54:57], v[34:49]
	s_waitcnt lgkmcnt(5)
	v_mfma_f32_32x32x16_bf16 v[34:49], v[196:199], v[62:65], v[34:49]
	s_waitcnt lgkmcnt(4)
	v_mfma_f32_32x32x16_bf16 v[34:49], v[200:203], v[66:69], v[34:49]
	s_nop 11
	v_max_f32_e32 v142, v34, v34
	v_max_f32_e32 v141, v35, v35
	v_max_f32_e32 v140, v36, v36
	v_max_f32_e32 v139, v37, v37
	v_max_f32_e32 v138, v38, v38
	v_max_f32_e32 v137, v39, v39
	v_max_f32_e32 v136, v40, v40
	v_max_f32_e32 v135, v41, v41
	v_max_f32_e32 v134, v42, v42
	v_max_f32_e32 v133, v43, v43
	v_max_f32_e32 v132, v44, v44
	v_max_f32_e32 v131, v45, v45
	v_max_f32_e32 v130, v46, v46
	v_max_f32_e32 v46, v47, v47
	v_max_f32_e32 v45, v48, v48
	v_max_f32_e32 v44, v49, v49
	s_cbranch_scc0 .LBB0_225
	v_min_f32_e32 v34, 0x41700000, v142
	v_exp_f32_e32 v34, v34
	v_add_u32_e32 v145, 64, v126
	v_min_f32_e32 v35, 0x41700000, v141
	v_cmp_lt_i32_e32 vcc, 0, v145
	v_exp_f32_e32 v35, v35
	v_min_f32_e32 v36, 0x41700000, v139
	v_cndmask_b32_e32 v38, 0, v34, vcc
	v_min_f32_e32 v34, 0x41700000, v140
	v_exp_f32_e32 v34, v34
	v_exp_f32_e32 v36, v36
	v_cmp_lt_i32_e32 vcc, 1, v145
	v_min_f32_e32 v39, 0x41700000, v133
	v_exp_f32_e32 v47, v39
	v_cndmask_b32_e32 v35, 0, v35, vcc
	v_cmp_lt_i32_e32 vcc, 2, v145
	v_min_f32_e32 v48, 0x41700000, v131
	v_exp_f32_e32 v48, v48
	v_cndmask_b32_e32 v40, 0, v34, vcc
	v_cmp_lt_i32_e32 vcc, 3, v145
	v_min_f32_e32 v34, 0x41700000, v138
	v_exp_f32_e32 v34, v34
	v_cndmask_b32_e32 v37, 0, v36, vcc
	v_min_f32_e32 v36, 0x41700000, v137
	v_exp_f32_e32 v36, v36
	v_cmp_lt_i32_e32 vcc, 4, v145
	v_min_f32_e32 v143, 0x41700000, v46
	v_exp_f32_e32 v143, v143
	v_cndmask_b32_e32 v42, 0, v34, vcc
	v_cmp_lt_i32_e32 vcc, 5, v145
	v_min_f32_e32 v34, 0x41700000, v136
	v_exp_f32_e32 v34, v34
	v_cndmask_b32_e32 v41, 0, v36, vcc
	v_min_f32_e32 v36, 0x41700000, v135
	v_exp_f32_e32 v36, v36
	v_cmp_lt_i32_e32 vcc, 6, v145
	v_min_f32_e32 v146, 0x41700000, v44
	v_exp_f32_e32 v146, v146
	v_cndmask_b32_e32 v34, 0, v34, vcc
	v_cmp_lt_i32_e32 vcc, 7, v145
	s_mov_b64 s[44:45], 0
	s_nop 0
	v_cndmask_b32_e32 v43, 0, v36, vcc
	v_min_f32_e32 v36, 0x41700000, v134
	v_exp_f32_e32 v36, v36
	v_cmp_lt_i32_e32 vcc, 8, v145
	s_nop 1
	v_cndmask_b32_e32 v39, 0, v36, vcc
	v_min_f32_e32 v36, 0x41700000, v132
	v_exp_f32_e32 v36, v36
	v_cmp_lt_i32_e32 vcc, 9, v145
	s_nop 1
	v_cndmask_b32_e32 v47, 0, v47, vcc
	v_cmp_lt_i32_e32 vcc, 10, v145
	s_nop 1
	v_cndmask_b32_e32 v49, 0, v36, vcc
	v_min_f32_e32 v36, 0x41700000, v130
	v_exp_f32_e32 v36, v36
	v_cmp_lt_i32_e32 vcc, 11, v145
	s_nop 1
	v_cndmask_b32_e32 v48, 0, v48, vcc
	v_cmp_lt_i32_e32 vcc, 12, v145
	s_nop 1
	v_cndmask_b32_e32 v144, 0, v36, vcc
	v_min_f32_e32 v36, 0x41700000, v45
	v_exp_f32_e32 v36, v36
	v_cmp_lt_i32_e32 vcc, 13, v145
	s_nop 1
	v_cndmask_b32_e32 v143, 0, v143, vcc
	v_cmp_lt_i32_e32 vcc, 14, v145
	s_nop 1
	v_cndmask_b32_e32 v36, 0, v36, vcc
	v_cmp_lt_i32_e32 vcc, 15, v145
	s_nop 1
	v_cndmask_b32_e32 v145, 0, v146, vcc

.LBB0_227:
	v_add_f32_e32 v44, 1.0, v38
	v_add_f32_e32 v46, 1.0, v39
	v_mul_f32_e32 v130, v35, v44
	v_fmac_f32_e32 v44, v44, v35
	v_mul_f32_e32 v131, v47, v46
	v_fmac_f32_e32 v46, v46, v47
	v_mul_f32_e32 v132, v40, v44
	v_fmac_f32_e32 v44, v44, v40
	v_mul_f32_e32 v133, v49, v46
	v_fmac_f32_e32 v46, v46, v49
	v_mul_f32_e32 v49, v37, v44
	v_fmac_f32_e32 v44, v44, v37
	v_mul_f32_e32 v134, v48, v46
	v_fmac_f32_e32 v46, v46, v48
	v_mul_f32_e32 v48, v42, v44
	v_fmac_f32_e32 v44, v44, v42
	v_mul_f32_e32 v135, v144, v46
	v_fmac_f32_e32 v46, v46, v144
	v_mul_f32_e32 v136, v41, v44
	v_fmac_f32_e32 v44, v44, v41
	v_mul_f32_e32 v137, v143, v46
	v_fmac_f32_e32 v46, v46, v143
	v_fma_f32 v35, v44, v34, v44
	v_fma_f32 v37, v46, v36, v46
	v_mul_f32_e32 v138, v43, v35
	v_fmac_f32_e32 v35, v35, v43
	v_mul_f32_e32 v139, v145, v37
	v_fmac_f32_e32 v37, v37, v145
	v_rcp_f32_e32 v45, v35
	v_rcp_f32_e32 v37, v37
	v_and_b32_e32 v41, 64, v191
	v_xor_b32_e32 v40, 32, v191
	v_add_u32_e32 v41, 64, v41
	v_cmp_lt_i32_e32 vcc, v40, v41
	v_mul_f32_e32 v35, v37, v45
	s_nop 0
	v_cndmask_b32_e32 v40, v191, v40, vcc
	v_lshlrev_b32_e32 v40, 2, v40
	ds_bpermute_b32 v40, v40, v35
	v_mul_f32_e32 v35, v95, v35
	s_waitcnt lgkmcnt(0)
	v_mul_f32_e32 v41, v95, v40
	v_cndmask_b32_e64 v47, v95, v41, s[2:3]
	v_pk_mul_f32 v[42:43], v[36:37], v[46:47]
	v_mul_f32_e32 v95, v35, v40
	v_mov_b32_e32 v35, v43
	v_pk_mul_f32 v[40:41], v[34:35], v[44:45]
	v_add_u32_e32 v46, v83, v120
	v_mul_f32_e32 v34, v38, v41
	v_mul_f32_e32 v35, v130, v41
	v_cvt_pk_bf16_f32 v34, v34, v35
	v_mul_f32_e32 v35, v132, v41
	v_mul_f32_e32 v36, v49, v41
	v_cvt_pk_bf16_f32 v35, v35, v36
	v_mul_f32_e32 v36, v48, v41
	v_mul_f32_e32 v37, v136, v41
	v_cvt_pk_bf16_f32 v36, v36, v37
	v_mul_f32_e32 v37, v40, v41
	v_mul_f32_e32 v38, v138, v41
	v_cvt_pk_bf16_f32 v37, v37, v38
	v_mul_f32_e32 v38, v39, v43
	v_mul_f32_e32 v39, v131, v43
	v_cvt_pk_bf16_f32 v38, v38, v39
	v_mul_f32_e32 v39, v133, v43
	v_mul_f32_e32 v40, v134, v43
	v_cvt_pk_bf16_f32 v39, v39, v40
	v_mul_f32_e32 v40, v135, v43
	v_mul_f32_e32 v41, v137, v43
	v_cvt_pk_bf16_f32 v40, v40, v41
	v_mul_f32_e32 v41, v42, v43
	v_mul_f32_e32 v42, v139, v43
	v_cvt_pk_bf16_f32 v41, v41, v42
	v_add_u32_e32 v47, v83, v121
	s_nop 1
	s_waitcnt lgkmcnt(0)
	v_mfma_f32_32x32x16_bf16 v[16:31], v[204:207], v[34:37], v[16:31]
	v_mfma_f32_32x32x16_bf16 v[16:31], v[208:211], v[38:41], v[16:31]
	v_mfma_f32_32x32x16_bf16 v[0:15], v[212:215], v[34:37], v[0:15]
	v_mfma_f32_32x32x16_bf16 v[0:15], v[216:219], v[38:41], v[0:15]
.LBB0_228:
	ds_read_b128 v[34:37], v129 offset:16384
	ds_read_b128 v[128:131], v128 offset:16384
	ds_read_b128 v[222:225], v127 offset:16384
	ds_read_b128 v[226:229], v33 offset:16384
	v_add_u32_e32 v246, v83, v122
	v_add_u32_e32 v247, v83, v123
	ds_read_b128 v[230:233], v246 offset:24576
	ds_read_b128 v[234:237], v247 offset:24576
	ds_read_b128 v[238:241], v246 offset:28672
	ds_read_b128 v[242:245], v247 offset:28672
	s_add_i32 s46, s91, 31
	s_mov_b64 s[44:45], -1
	s_cmp_lt_i32 s46, s38
	s_waitcnt lgkmcnt(7)
	v_mfma_f32_32x32x16_bf16 v[34:49], v[34:37], v[50:53], 0
	s_waitcnt lgkmcnt(6)
	v_mfma_f32_32x32x16_bf16 v[34:49], v[128:131], v[54:57], v[34:49]
	s_waitcnt lgkmcnt(5)
	v_mfma_f32_32x32x16_bf16 v[34:49], v[222:225], v[62:65], v[34:49]
	s_waitcnt lgkmcnt(4)
	v_mfma_f32_32x32x16_bf16 v[34:49], v[226:229], v[66:69], v[34:49]
	s_nop 11
	v_max_f32_e32 v138, v34, v34
	v_max_f32_e32 v137, v35, v35
	v_max_f32_e32 v136, v36, v36
	v_max_f32_e32 v135, v37, v37
	v_max_f32_e32 v134, v38, v38
	v_max_f32_e32 v133, v39, v39
	v_max_f32_e32 v132, v40, v40
	v_max_f32_e32 v131, v41, v41
	v_max_f32_e32 v130, v42, v42
	v_max_f32_e32 v129, v43, v43
	v_max_f32_e32 v128, v44, v44
	v_max_f32_e32 v127, v45, v45
	v_max_f32_e32 v46, v46, v46
	v_max_f32_e32 v45, v47, v47
	v_max_f32_e32 v44, v48, v48
	v_max_f32_e32 v43, v49, v49
	s_cbranch_scc1 .LBB0_230
	v_min_f32_e32 v33, 0x41700000, v138
	v_exp_f32_e32 v33, v33
	v_min_f32_e32 v34, 0x41700000, v137
	v_exp_f32_e32 v34, v34
	v_add_u32_e32 v141, 0x60, v126
	v_cmp_lt_i32_e32 vcc, 0, v141
	v_min_f32_e32 v36, 0x41700000, v135
	v_exp_f32_e32 v36, v36
	v_cndmask_b32_e32 v33, 0, v33, vcc
	v_cmp_lt_i32_e32 vcc, 1, v141
	v_min_f32_e32 v38, 0x41700000, v129
	v_exp_f32_e32 v47, v38
	v_cndmask_b32_e32 v35, 0, v34, vcc
	v_min_f32_e32 v34, 0x41700000, v136
	v_exp_f32_e32 v34, v34
	v_cmp_lt_i32_e32 vcc, 2, v141
	v_min_f32_e32 v48, 0x41700000, v127
	v_exp_f32_e32 v48, v48
	v_cndmask_b32_e32 v39, 0, v34, vcc
	v_cmp_lt_i32_e32 vcc, 3, v141
	v_min_f32_e32 v34, 0x41700000, v134
	v_exp_f32_e32 v34, v34
	v_cndmask_b32_e32 v37, 0, v36, vcc
	v_min_f32_e32 v36, 0x41700000, v133
	v_exp_f32_e32 v36, v36
	v_cmp_lt_i32_e32 vcc, 4, v141
	v_min_f32_e32 v139, 0x41700000, v45
	v_exp_f32_e32 v139, v139
	v_cndmask_b32_e32 v41, 0, v34, vcc
	v_cmp_lt_i32_e32 vcc, 5, v141
	v_min_f32_e32 v34, 0x41700000, v132
	v_exp_f32_e32 v34, v34
	v_cndmask_b32_e32 v40, 0, v36, vcc
	v_min_f32_e32 v36, 0x41700000, v131
	v_exp_f32_e32 v36, v36
	v_cmp_lt_i32_e32 vcc, 6, v141
	v_min_f32_e32 v142, 0x41700000, v43
	v_exp_f32_e32 v142, v142
	v_cndmask_b32_e32 v34, 0, v34, vcc
	v_cmp_lt_i32_e32 vcc, 7, v141
	s_mov_b64 s[44:45], 0
	s_nop 0
	v_cndmask_b32_e32 v42, 0, v36, vcc
	v_min_f32_e32 v36, 0x41700000, v130
	v_exp_f32_e32 v36, v36
	v_cmp_lt_i32_e32 vcc, 8, v141
	s_nop 1
	v_cndmask_b32_e32 v38, 0, v36, vcc
	v_min_f32_e32 v36, 0x41700000, v128
	v_exp_f32_e32 v36, v36
	v_cmp_lt_i32_e32 vcc, 9, v141
	s_nop 1
	v_cndmask_b32_e32 v47, 0, v47, vcc
	v_cmp_lt_i32_e32 vcc, 10, v141
	s_nop 1
	v_cndmask_b32_e32 v49, 0, v36, vcc
	v_min_f32_e32 v36, 0x41700000, v46
	v_exp_f32_e32 v36, v36
	v_cmp_lt_i32_e32 vcc, 11, v141
	s_nop 1
	v_cndmask_b32_e32 v48, 0, v48, vcc
	v_cmp_lt_i32_e32 vcc, 12, v141
	s_nop 1
	v_cndmask_b32_e32 v140, 0, v36, vcc
	v_min_f32_e32 v36, 0x41700000, v44
	v_exp_f32_e32 v36, v36
	v_cmp_lt_i32_e32 vcc, 13, v141
	s_nop 1
	v_cndmask_b32_e32 v139, 0, v139, vcc
	v_cmp_lt_i32_e32 vcc, 14, v141
	s_nop 1
	v_cndmask_b32_e32 v36, 0, v36, vcc
	v_cmp_lt_i32_e32 vcc, 15, v141
	s_nop 1
	v_cndmask_b32_e32 v141, 0, v142, vcc
